# sliding-window attention: row-major V image with transpose reads, staging loads all in flight
# baseline (speedup 1.0000x reference)
.LBB0_463:
	s_or_b64 exec, exec, s[28:29]
	s_and_b32 s39, s34, 3
	v_ashrrev_i32_e32 v70, 7, v16
	s_lshl_b32 s47, s39, 2
	v_add_u32_e32 v71, s47, v70
	v_lshl_add_u32 v0, v0, 4, v71
	v_readlane_b32 s80, v241, 56
	v_ashrrev_i32_e32 v1, 31, v0
	v_readlane_b32 s88, v240, 0
	v_readlane_b32 s89, v240, 1
	v_and_b32_e32 v72, 7, v16
	s_mov_b64 s[28:29], -1
	v_lshl_add_u64 v[0:1], v[0:1], 2, s[88:89]
	global_load_dword v1, v[0:1], off
	v_lshl_add_u32 v0, v16, 2, 0
	v_add_u32_e32 v2, 0x10000, v0
	v_lshlrev_b32_e32 v0, 3, v72
	v_lshlrev_b32_e32 v8, 4, v72
	v_lshl_add_u32 v17, v72, 12, 0
	s_andn2_b64 vcc, exec, s[0:1]
	v_and_b32_e32 v18, 24, v0
	v_or_b32_e32 v13, 1, v0
	v_bitop3_b32 v19, v0, 25, 1 bitop3:0xc8
	v_or_b32_e32 v14, 2, v0
	v_bitop3_b32 v20, v0, 26, 2 bitop3:0xc8
	v_or_b32_e32 v15, 3, v0
	v_bitop3_b32 v21, v0, 27, 3 bitop3:0xc8
	v_or_b32_e32 v26, 4, v0
	v_bitop3_b32 v22, v0, 28, 4 bitop3:0xc8
	v_or_b32_e32 v27, 5, v0
	v_bitop3_b32 v23, v0, 29, 5 bitop3:0xc8
	v_or_b32_e32 v28, 6, v0
	v_bitop3_b32 v24, v0, 30, 6 bitop3:0xc8
	v_or_b32_e32 v29, 7, v0
	v_bitop3_b32 v25, v0, 31, 7 bitop3:0xc8
	v_readlane_b32 s81, v241, 57
	v_readlane_b32 s82, v241, 58
	v_readlane_b32 s83, v241, 59
	v_readlane_b32 s84, v241, 60
	v_readlane_b32 s85, v241, 61
	v_readlane_b32 s86, v241, 62
	v_readlane_b32 s87, v241, 63
	v_readlane_b32 s90, v240, 2
	v_readlane_b32 s91, v240, 3
	v_readlane_b32 s92, v240, 4
	v_readlane_b32 s93, v240, 5
	v_readlane_b32 s94, v240, 6
	v_readlane_b32 s95, v240, 7
	s_waitcnt vmcnt(0)
	ds_write_b32 v2, v1
	s_cbranch_vccnz .LBB0_477
	v_readlane_b32 s28, v241, 46
	v_readlane_b32 s29, v241, 47
	v_readlane_b32 s30, v241, 48
	v_readlane_b32 s31, v241, 49
	v_readlane_b32 s0, v243, 32
	v_readlane_b32 s1, v243, 33
	v_lshrrev_b32_e32 v170, 3, v16
	v_and_b32_e32 v171, 7, v16
	v_bfe_u32 v173, v170, 1, 3
	v_xor_b32_e32 v173, v173, v171
	v_lshlrev_b32_e32 v173, 4, v173
	v_lshl_add_u32 v173, v170, 7, v173
	v_bfe_u32 v174, v170, 1, 1
	v_lshlrev_b32_e32 v174, 2, v174
	v_xor_b32_e32 v174, v174, v171
	v_lshlrev_b32_e32 v174, 4, v174
	v_lshl_add_u32 v174, v170, 7, v174
	v_add_u32_e32 v174, 0x8000, v174
	s_lshl_b32 s48, s39, 7
	s_add_u32 s0, s0, s48
	s_addc_u32 s1, s1, 0
	s_lshl_b32 s49, s38, 7
	v_add_u32_e32 v172, s49, v170
	v_lshlrev_b32_e32 v172, 10, v172
	s_lshl_b32 s48, s39, 8
	v_lshl_add_u32 v175, v171, 5, s48
	v_add_u32_e32 v172, v172, v175
	v_mov_b32_e32 v208, 0
	v_mov_b32_e32 v209, 0
	v_mov_b32_e32 v210, 0
	v_mov_b32_e32 v211, 0
	v_mov_b32_e32 v212, 0
	v_mov_b32_e32 v213, 0
	v_mov_b32_e32 v214, 0
	v_mov_b32_e32 v215, 0
	s_mov_b64 s[50:51], exec
	v_cmp_gt_u32_e32 vcc, 64, v16
	s_and_b64 exec, s[50:51], vcc
	s_cbranch_execz .Lswa_s_noload
	s_lshl_b32 s48, s38, 3
	s_addk_i32 s48, 0x4000
	v_add_u32_e32 v175, s48, v170
	v_lshlrev_b32_e32 v175, 10, v175
	v_lshl_add_u32 v175, v171, 4, v175
	global_load_dwordx4 v[208:211], v175, s[0:1]
	global_load_dwordx4 v[212:215], v175, s[0:1] offset:512
.Lswa_s_noload:
	s_mov_b64 exec, s[50:51]
	global_load_dwordx4 v[176:179], v172, s[28:29]
	global_load_dwordx4 v[180:183], v172, s[28:29] offset:16
	global_load_dwordx4 v[184:187], v172, s[30:31]
	global_load_dwordx4 v[188:191], v172, s[30:31] offset:16
	v_add_u32_e32 v172, 0x10000, v172
	global_load_dwordx4 v[192:195], v172, s[28:29]
	global_load_dwordx4 v[196:199], v172, s[28:29] offset:16
	global_load_dwordx4 v[200:203], v172, s[30:31]
	global_load_dwordx4 v[204:207], v172, s[30:31] offset:16
	s_waitcnt vmcnt(4)
	v_cvt_pk_bf16_f32 v176, v176, v177
	v_cvt_pk_bf16_f32 v177, v178, v179
	v_cvt_pk_bf16_f32 v178, v180, v181
	v_cvt_pk_bf16_f32 v179, v182, v183
	v_cvt_pk_bf16_f32 v184, v184, v185
	v_cvt_pk_bf16_f32 v185, v186, v187
	v_cvt_pk_bf16_f32 v186, v188, v189
	v_cvt_pk_bf16_f32 v187, v190, v191
	ds_write_b128 v173, v[176:179]
	ds_write_b128 v174, v[184:187]
	s_waitcnt vmcnt(0)
	v_cvt_pk_bf16_f32 v192, v192, v193
	v_cvt_pk_bf16_f32 v193, v194, v195
	v_cvt_pk_bf16_f32 v194, v196, v197
	v_cvt_pk_bf16_f32 v195, v198, v199
	v_cvt_pk_bf16_f32 v200, v200, v201
	v_cvt_pk_bf16_f32 v201, v202, v203
	v_cvt_pk_bf16_f32 v202, v204, v205
	v_cvt_pk_bf16_f32 v203, v206, v207
	ds_write_b128 v173, v[192:195] offset:8192
	ds_write_b128 v174, v[200:203] offset:8192
	v_cmp_gt_u32_e32 vcc, 0x100, v16
	s_and_b64 exec, s[50:51], vcc
	s_cbranch_execz .Lswa_s_done
	ds_write_b128 v173, v[208:211] offset:16384
	ds_write_b128 v174, v[212:215] offset:16384
.Lswa_s_done:
	s_mov_b64 exec, s[50:51]
	s_branch .LBB0_476

.LBB0_477:
	s_and_b64 vcc, exec, s[28:29]
	s_cbranch_vccz .LBB0_484
	v_readlane_b32 s48, v243, 32
	v_readlane_b32 s49, v243, 33
	v_lshrrev_b32_e32 v170, 3, v16
	v_and_b32_e32 v171, 7, v16
	v_bfe_u32 v173, v170, 1, 3
	v_xor_b32_e32 v173, v173, v171
	v_lshlrev_b32_e32 v173, 4, v173
	v_lshl_add_u32 v173, v170, 7, v173
	v_bfe_u32 v174, v170, 1, 1
	v_lshlrev_b32_e32 v174, 2, v174
	v_xor_b32_e32 v174, v174, v171
	v_lshlrev_b32_e32 v174, 4, v174
	v_lshl_add_u32 v174, v170, 7, v174
	v_add_u32_e32 v174, 0x8000, v174
	s_lshl_b32 s28, s38, 13
	s_lshl_b32 s29, s46, 7
	s_or_b32 s31, s29, s28
	s_addk_i32 s31, 0xff80
	s_lshl_b32 s28, s39, 7
	s_add_u32 s28, s48, s28
	s_addc_u32 s29, s49, 0
	v_add_u32_e32 v172, s31, v170
	v_lshlrev_b32_e32 v172, 10, v172
	v_lshl_add_u32 v172, v171, 4, v172
	v_add_u32_e32 v175, 0x20000, v172
	global_load_dwordx4 v[192:195], v175, s[28:29]
	global_load_dwordx4 v[196:199], v175, s[28:29] offset:512
	v_add_u32_e32 v175, 0x10000, v175
	global_load_dwordx4 v[200:203], v175, s[28:29]
	global_load_dwordx4 v[204:207], v175, s[28:29] offset:512
	s_cmp_eq_u32 s46, 0
	s_cbranch_scc1 .Lswa_p_first
	global_load_dwordx4 v[176:179], v172, s[28:29]
	global_load_dwordx4 v[180:183], v172, s[28:29] offset:512
	v_add_u32_e32 v172, 0x10000, v172
	global_load_dwordx4 v[184:187], v172, s[28:29]
	global_load_dwordx4 v[188:191], v172, s[28:29] offset:512
	s_branch .Lswa_p_write
.Lswa_p_first:
	v_mov_b32_e32 v176, 0
	v_mov_b32_e32 v177, 0
	v_mov_b32_e32 v178, 0
	v_mov_b32_e32 v179, 0
	v_mov_b32_e32 v180, 0
	v_mov_b32_e32 v181, 0
	v_mov_b32_e32 v182, 0
	v_mov_b32_e32 v183, 0
	v_mov_b32_e32 v184, 0
	v_mov_b32_e32 v185, 0
	v_mov_b32_e32 v186, 0
	v_mov_b32_e32 v187, 0
	v_mov_b32_e32 v188, 0
	v_mov_b32_e32 v189, 0
	v_mov_b32_e32 v190, 0
	v_mov_b32_e32 v191, 0
.Lswa_p_write:
	s_waitcnt vmcnt(0)
	ds_write_b128 v173, v[176:179]
	ds_write_b128 v174, v[180:183]
	ds_write_b128 v173, v[184:187] offset:8192
	ds_write_b128 v174, v[188:191] offset:8192
	ds_write_b128 v173, v[192:195] offset:16384
	ds_write_b128 v174, v[196:199] offset:16384
	ds_write_b128 v173, v[200:203] offset:24576
	ds_write_b128 v174, v[204:207] offset:24576

.LBB0_489:
	s_movk_i32 s0, 0x600
	v_mad_u64_u32 v[66:67], s[0:1], v1, s0, 0
	v_readlane_b32 s0, v243, 52
	v_readlane_b32 s1, v243, 53
	v_lshlrev_b32_e32 v68, 6, v0
	v_ashrrev_i32_e32 v69, 31, v68
	v_lshl_add_u64 v[4:5], v[66:67], 1, s[0:1]
	v_ashrrev_i32_e32 v1, 31, v0
	v_lshl_add_u64 v[4:5], v[68:69], 1, v[4:5]
	v_lshl_add_u64 v[0:1], v[0:1], 2, s[8:9]
	v_lshl_add_u64 v[4:5], v[4:5], 0, v[136:137]
	global_load_dword v90, v[0:1], off
	global_load_dwordx4 v[48:51], v[4:5], off
	global_load_dwordx4 v[52:55], v[4:5], off offset:32
	global_load_dwordx4 v[56:59], v[4:5], off offset:64
	global_load_dwordx4 v[60:63], v[4:5], off offset:96
	s_add_i32 s0, 0, 0x10000
	v_lshlrev_b32_e32 v31, 5, v3
	v_add_u32_e32 v32, v88, v2
	v_lshl_or_b32 v91, v3, 3, v85
	v_lshl_add_u32 v92, v3, 12, v89
	s_mov_b32 s48, 0
	v_mov_b32_e32 v0, 0
	v_mov_b32_e32 v1, v65
	v_mov_b32_e32 v2, v65
	v_mov_b32_e32 v3, v65
	v_mov_b32_e32 v4, v65
	v_mov_b32_e32 v5, v65
	v_mov_b32_e32 v6, v65
	v_mov_b32_e32 v7, v65
	v_mov_b32_e32 v8, v65
	v_mov_b32_e32 v9, v65
	v_mov_b32_e32 v10, v65
	v_mov_b32_e32 v11, v65
	v_mov_b32_e32 v12, v65
	v_mov_b32_e32 v13, v65
	v_mov_b32_e32 v14, v65
	v_mov_b32_e32 v15, v65
	v_mov_b32_e32 v16, 0
	v_mov_b32_e32 v17, v65
	v_mov_b32_e32 v18, v65
	v_mov_b32_e32 v19, v65
	v_mov_b32_e32 v20, v65
	v_mov_b32_e32 v21, v65
	v_mov_b32_e32 v22, v65
	v_mov_b32_e32 v23, v65
	v_mov_b32_e32 v24, v65
	v_mov_b32_e32 v25, v65
	v_mov_b32_e32 v26, v65
	v_mov_b32_e32 v27, v65
	v_mov_b32_e32 v28, v65
	v_mov_b32_e32 v29, v65
	v_lshl_add_u32 v93, v30, 9, s0
	v_or_b32_e32 v94, v79, v31
	v_sub_u32_e32 v95, v32, v31
	v_mov_b32_e32 v30, v65
	v_mov_b32_e32 v31, v65
	s_waitcnt vmcnt(4)
	v_mov_b32_e32 v96, v90
	v_bfe_u32 v218, v164, 2, 2
	v_and_b32_e32 v219, 3, v164
	v_lshlrev_b32_e32 v214, 7, v218
	v_lshl_add_u32 v214, v219, 3, v214
	v_bfe_u32 v219, v164, 4, 1
	v_lshl_add_u32 v214, v219, 5, v214
	v_lshrrev_b32_e32 v219, 5, v164
	v_lshl_add_u32 v214, v219, 9, v214
	v_add_u32_e32 v214, 0x8000, v214
	v_sub_u32_e32 v219, v92, v89
	v_add_u32_e32 v214, v214, v219
	v_lshrrev_b32_e32 v218, 1, v218
	v_lshl_add_u32 v216, v218, 6, v214
	v_xor_b32_e32 v218, 1, v218
	v_lshl_add_u32 v217, v218, 6, v214

.Lswa_sc_done:
	v_max3_f32 v38, v98, s33, v97
	v_max3_f32 v38, v38, v33, v32
	v_max3_f32 v38, v38, v35, v34
	v_max3_f32 v38, v38, v37, v36
	v_max3_f32 v38, v38, v100, v39
	v_max3_f32 v38, v38, v41, v40
	v_max3_f32 v38, v38, v43, v42
	v_max3_f32 v38, v38, v45, v44
	ds_bpermute_b32 v46, v80, v38
	s_add_i32 s48, s48, 32
	v_subrev_u32_e32 v95, 32, v95
	s_cmpk_lg_i32 s48, 0xa0
	v_add_u32_e32 v92, 0x1000, v92
	s_waitcnt lgkmcnt(0)
	v_max3_f32 v38, v96, v38, v46
	v_sub_f32_e32 v32, v32, v38
	v_mul_f32_e32 v32, 0x3fb8aa3b, v32
	v_exp_f32_e32 v105, v32
	v_sub_f32_e32 v32, v35, v38
	v_mul_f32_e32 v32, 0x3fb8aa3b, v32
	v_exp_f32_e32 v106, v32
	v_sub_f32_e32 v32, v34, v38
	v_mul_f32_e32 v32, 0x3fb8aa3b, v32
	v_exp_f32_e32 v107, v32
	v_sub_f32_e32 v32, v37, v38
	v_mul_f32_e32 v32, 0x3fb8aa3b, v32
	v_exp_f32_e32 v37, v32
	v_sub_f32_e32 v32, v36, v38
	v_mul_f32_e32 v32, 0x3fb8aa3b, v32
	v_exp_f32_e32 v36, v32
	v_sub_f32_e32 v32, v100, v38
	v_mul_f32_e32 v32, 0x3fb8aa3b, v32
	v_exp_f32_e32 v100, v32
	v_sub_f32_e32 v32, v39, v38
	v_mul_f32_e32 v32, 0x3fb8aa3b, v32
	v_exp_f32_e32 v39, v32
	v_sub_f32_e32 v32, v41, v38
	v_mul_f32_e32 v32, 0x3fb8aa3b, v32
	v_exp_f32_e32 v108, v32
	v_sub_f32_e32 v32, v40, v38
	v_mul_f32_e32 v32, 0x3fb8aa3b, v32
	v_sub_f32_e32 v46, v96, v38
	v_exp_f32_e32 v109, v32
	v_sub_f32_e32 v32, v43, v38
	v_mul_f32_e32 v46, 0x3fb8aa3b, v46
	v_mul_f32_e32 v32, 0x3fb8aa3b, v32
	v_exp_f32_e32 v102, v46
	v_sub_f32_e32 v46, v98, v38
	v_exp_f32_e32 v110, v32
	v_sub_f32_e32 v32, v42, v38
	v_add_u32_e32 v34, -6, v91
	v_mul_f32_e32 v46, 0x3fb8aa3b, v46
	v_mul_f32_e32 v32, 0x3fb8aa3b, v32
	v_xor_b32_e32 v34, v34, v74
	v_add_u32_e32 v35, -4, v91
	v_exp_f32_e32 v101, v46
	v_sub_f32_e32 v46, v97, v38
	v_exp_f32_e32 v111, v32
	v_sub_f32_e32 v32, v45, v38
	v_xor_b32_e32 v35, v35, v74
	v_lshl_add_u32 v34, v34, 3, v81
	v_mul_f32_e32 v46, 0x3fb8aa3b, v46
	v_mul_f32_e32 v32, 0x3fb8aa3b, v32
	ds_read_b64_tr_b16 v[40:41], v216
	ds_read_b64_tr_b16 v[42:43], v217
	v_lshl_add_u32 v34, v35, 3, v81
	v_pk_mul_f32 v[14:15], v[14:15], v[102:103] op_sel_hi:[1,0]
	v_pk_mul_f32 v[12:13], v[12:13], v[102:103] op_sel_hi:[1,0]
	v_pk_mul_f32 v[10:11], v[10:11], v[102:103] op_sel_hi:[1,0]
	v_pk_mul_f32 v[8:9], v[8:9], v[102:103] op_sel_hi:[1,0]
	v_pk_mul_f32 v[6:7], v[6:7], v[102:103] op_sel_hi:[1,0]
	v_pk_mul_f32 v[4:5], v[4:5], v[102:103] op_sel_hi:[1,0]
	v_pk_mul_f32 v[2:3], v[2:3], v[102:103] op_sel_hi:[1,0]
	v_pk_mul_f32 v[0:1], v[0:1], v[102:103] op_sel_hi:[1,0]
	v_exp_f32_e32 v103, v46
	v_exp_f32_e32 v112, v32
	v_sub_f32_e32 v32, v44, v38
	ds_read_b64_tr_b16 v[44:45], v216 offset:1024
	ds_read_b64_tr_b16 v[46:47], v217 offset:1024
	s_waitcnt lgkmcnt(2)
	v_mov_b32_e32 v96, v40
	v_mov_b32_e32 v97, v41
	v_sub_f32_e32 v33, v33, v38
	v_mul_f32_e32 v33, 0x3fb8aa3b, v33
	s_waitcnt lgkmcnt(0)
	v_mov_b32_e32 v98, v44
	v_mov_b32_e32 v99, v45
	v_pk_mul_f32 v[30:31], v[30:31], v[102:103] op_sel_hi:[1,0]
	v_pk_mul_f32 v[28:29], v[28:29], v[102:103] op_sel_hi:[1,0]
	v_pk_mul_f32 v[26:27], v[26:27], v[102:103] op_sel_hi:[1,0]
	v_pk_mul_f32 v[24:25], v[24:25], v[102:103] op_sel_hi:[1,0]
	v_pk_mul_f32 v[22:23], v[22:23], v[102:103] op_sel_hi:[1,0]
	v_pk_mul_f32 v[20:21], v[20:21], v[102:103] op_sel_hi:[1,0]
	v_pk_mul_f32 v[18:19], v[18:19], v[102:103] op_sel_hi:[1,0]
	v_pk_mul_f32 v[16:17], v[16:17], v[102:103] op_sel_hi:[1,0]
	v_add_u32_e32 v40, -2, v91
	v_exp_f32_e32 v104, v33
	v_mul_f32_e32 v113, 0x3fb8aa3b, v32
	v_cvt_pk_bf16_f32 v32, v101, v103
	v_cvt_pk_bf16_f32 v33, v104, v105
	v_cvt_pk_bf16_f32 v34, v106, v107
	v_cvt_pk_bf16_f32 v35, v37, v36
	v_xor_b32_e32 v40, v40, v74
	v_mfma_f32_32x32x16_bf16 v[16:31], v[96:99], v[32:35], v[16:31]
	v_xor_b32_e32 v96, v91, v74
	v_lshl_add_u32 v40, v40, 3, v81
	v_lshl_add_u32 v96, v96, 3, v81
	v_mov_b32_e32 v44, v42
	v_mov_b32_e32 v45, v43
	ds_read_b64_tr_b16 v[40:41], v216 offset:2048
	ds_read_b64_tr_b16 v[42:43], v217 offset:2048
	ds_read_b64_tr_b16 v[96:97], v216 offset:3072
	ds_read_b64_tr_b16 v[98:99], v217 offset:3072
	v_mfma_f32_32x32x16_bf16 v[0:15], v[44:47], v[32:35], v[0:15]
	s_waitcnt lgkmcnt(2)
	v_mov_b32_e32 v32, v40
	v_mov_b32_e32 v33, v41
	s_waitcnt lgkmcnt(0)
	v_mov_b32_e32 v34, v96
	v_mov_b32_e32 v35, v97
	v_fmac_f32_e32 v101, v65, v102
	v_exp_f32_e32 v113, v113
	v_cvt_pk_bf16_f32 v44, v100, v39
	v_cvt_pk_bf16_f32 v45, v108, v109
	v_cvt_pk_bf16_f32 v46, v110, v111
	v_cvt_pk_bf16_f32 v47, v112, v113
	v_mov_b32_e32 v96, v42
	v_mfma_f32_32x32x16_bf16 v[16:31], v[32:35], v[44:47], v[16:31]
	v_add_f32_e32 v32, v103, v101
	v_add_f32_e32 v32, v104, v32
	v_mov_b32_e32 v97, v43
	v_add_f32_e32 v32, v105, v32
	v_add_f32_e32 v32, v106, v32
	v_add_f32_e32 v32, v107, v32
	v_add_f32_e32 v32, v37, v32
	v_add_f32_e32 v32, v36, v32
	v_mfma_f32_32x32x16_bf16 v[0:15], v[96:99], v[44:47], v[0:15]
	v_add_f32_e32 v32, v100, v32
	v_add_f32_e32 v32, v39, v32
	v_add_f32_e32 v32, v108, v32
	v_add_f32_e32 v32, v109, v32
	v_add_f32_e32 v32, v110, v32
	v_add_f32_e32 v32, v111, v32
	v_add_f32_e32 v32, v112, v32
	v_add_f32_e32 v65, v113, v32
	v_add_u32_e32 v91, 8, v91
	v_add_u32_e32 v216, 0x1000, v216
	v_add_u32_e32 v217, 0x1000, v217
	s_cbranch_scc0 .LBB0_486
	v_mov_b32_e32 v96, v38
	s_branch .LBB0_490
